# gemm256 k-loops: LDS staging writes and next-tile global loads interleaved between MFMA groups
# speedup vs baseline: 1.0224x; 1.0224x over previous
.LBB0_80:
	s_mul_i32 s3, s33, s41
	s_mul_hi_u32 s2, s33, s41
	s_add_u32 s30, s3, s37
	s_addc_u32 s31, s2, 0
	s_lshr_b64 s[2:3], s[30:31], 2
	s_and_b32 s2, s2, -8
	s_or_b32 s31, s2, s35
	s_cmp_lt_i32 s31, 16
	s_cselect_b64 s[22:23], -1, 0
	s_cmp_gt_i32 s31, 15
	s_mov_b64 s[38:39], -1
	s_cbranch_scc1 .LBB0_79
	s_lshl_b32 s2, s31, 3
	s_and_b32 s3, s30, 7
	v_mov_b32_e32 v15, v1
	s_or_b32 s2, s2, s3
	s_ashr_i32 s3, s2, 31
	v_ashrrev_i32_e32 v3, 3, v15
	v_and_b32_e32 v4, 7, v15
	v_lshlrev_b32_e32 v2, 1, v3
	s_bfe_u32 s44, s30, 0x20003
	s_lshl_b64 s[30:31], s[2:3], 21
	v_lshlrev_b32_e32 v227, 3, v4
	v_and_b32_e32 v14, 24, v2
	v_lshrrev_b32_e32 v2, 2, v3
	v_lshlrev_b32_e32 v228, 12, v3
	s_add_u32 s30, s18, s30
	v_and_b32_e32 v16, 4, v2
	v_and_b32_e32 v17, 35, v3
	v_or_b32_e32 v2, v228, v227
	v_bitop3_b32 v3, v3, v15, 7 bitop3:0x78
	s_addc_u32 s31, s19, s31
	s_lshl_b32 s3, s44, 21
	v_or3_b32 v5, v17, v14, v16
	v_lshl_add_u32 v9, v4, 8, v3
	v_mov_b32_e32 v3, v34
	v_add_u32_e32 v6, 0x40000, v2
	v_mov_b32_e32 v7, v34
	s_add_u32 s38, s24, s3
	v_lshl_or_b32 v8, v5, 12, v227
	s_mov_b32 s3, 64
	v_lshl_add_u64 v[4:5], v[2:3], 1, s[30:31]
	v_lshl_add_u64 v[6:7], v[6:7], 1, s[30:31]
	global_load_dwordx4 v[124:127], v[4:5], off
	global_load_dwordx4 v[132:135], v[6:7], off
	v_add_u32_e32 v6, 0x80000, v2
	v_mov_b32_e32 v7, v34
	v_lshl_add_u64 v[6:7], v[6:7], 1, s[30:31]
	global_load_dwordx4 v[136:139], v[6:7], off
	v_add_u32_e32 v6, 0xc0000, v2
	v_mov_b32_e32 v7, v34
	v_lshl_add_u64 v[6:7], v[6:7], 1, s[30:31]
	global_load_dwordx4 v[140:143], v[6:7], off
	v_lshlrev_b32_e32 v6, 1, v8
	s_addc_u32 s39, s40, 0
	v_or_b32_e32 v8, 0x80000, v6
	v_or_b32_e32 v10, 0x100000, v6
	v_or_b32_e32 v12, 0x180000, v6
	global_load_dwordx4 v[144:147], v6, s[38:39]
	global_load_dwordx4 v[152:155], v8, s[38:39]
	global_load_dwordx4 v[156:159], v10, s[38:39]
	global_load_dwordx4 v[160:163], v12, s[38:39]
	v_lshl_add_u32 v229, v9, 4, 0
	v_add_u32_e32 v230, 0x10000, v229
	s_cmp_lt_i32 s3, 2
	s_waitcnt vmcnt(7)
	ds_write_b128 v229, v[124:127]
	s_waitcnt vmcnt(6)
	ds_write_b128 v229, v[132:135] offset:1024
	s_waitcnt vmcnt(5)
	ds_write_b128 v229, v[136:139] offset:2048
	s_waitcnt vmcnt(4)
	ds_write_b128 v229, v[140:143] offset:3072
	s_waitcnt vmcnt(3)
	ds_write_b128 v230, v[144:147]
	s_waitcnt vmcnt(2)
	ds_write_b128 v230, v[152:155] offset:1024
	s_waitcnt vmcnt(1)
	ds_write_b128 v230, v[156:159] offset:2048
	s_waitcnt vmcnt(0)
	ds_write_b128 v230, v[160:163] offset:3072
	s_cbranch_scc1 .LBB0_83
	v_add_u32_e32 v20, 0x80040, v2
	v_mov_b32_e32 v21, v34
	v_mov_b32_e32 v7, v34
	v_mov_b32_e32 v9, v34
	v_mov_b32_e32 v11, v34
	v_mov_b32_e32 v13, v34
	v_add_u32_e32 v18, 0x40040, v2
	v_mov_b32_e32 v19, v34
	v_lshl_add_u64 v[20:21], v[20:21], 1, s[30:31]
	v_add_u32_e32 v2, 0xc0040, v2
	v_mov_b32_e32 v3, v34
	v_lshl_add_u64 v[6:7], s[38:39], 0, v[6:7]
	v_lshl_add_u64 v[8:9], s[38:39], 0, v[8:9]
	v_lshl_add_u64 v[10:11], s[38:39], 0, v[10:11]
	v_lshl_add_u64 v[12:13], s[38:39], 0, v[12:13]
	v_lshl_add_u64 v[18:19], v[18:19], 1, s[30:31]
	v_lshl_add_u64 v[2:3], v[2:3], 1, s[30:31]
	global_load_dwordx4 v[124:127], v[4:5], off offset:128
	global_load_dwordx4 v[132:135], v[18:19], off
	global_load_dwordx4 v[136:139], v[20:21], off
	global_load_dwordx4 v[140:143], v[2:3], off
	global_load_dwordx4 v[144:147], v[6:7], off offset:128
	global_load_dwordx4 v[152:155], v[8:9], off offset:128
	global_load_dwordx4 v[156:159], v[10:11], off offset:128
	global_load_dwordx4 v[160:163], v[12:13], off offset:128

.LBB0_85:
	s_and_b32 s48, s45, 0x800
	s_lshl_b32 s47, s48, 4
	s_add_i32 s47, s47, 0
	s_add_i32 s49, s47, 0x10000
	v_add_u32_e32 v164, s47, v232
	v_add_u32_e32 v165, s49, v232
	v_add3_u32 v165, v165, v235, v236
	v_add3_u32 v208, v164, v233, v236
	ds_read_b128 v[176:179], v165
	ds_read_b128 v[180:183], v165 offset:256
	ds_read_b128 v[184:187], v165 offset:512
	ds_read_b128 v[188:191], v165 offset:768
	ds_read_b128 v[164:167], v208
	ds_read_b128 v[168:171], v208 offset:256
	ds_read_b128 v[172:175], v208 offset:512
	ds_read_b128 v[192:195], v208 offset:768
	ds_read_b128 v[196:199], v208 offset:1024
	ds_read_b128 v[200:203], v208 offset:1280
	ds_read_b128 v[204:207], v208 offset:1536
	ds_read_b128 v[208:211], v208 offset:1792
	v_add_u32_e32 v238, s47, v234
	v_add_u32_e32 v239, s49, v234
	v_add3_u32 v238, v238, v233, v237
	s_setprio 1
	s_waitcnt lgkmcnt(7)
	v_mfma_f32_16x16x32_f16 v[148:151], v[176:179], v[164:167], v[148:151]
	v_mfma_f32_16x16x32_f16 v[128:131], v[180:183], v[164:167], v[128:131]
	v_mfma_f32_16x16x32_f16 v[120:123], v[184:187], v[164:167], v[120:123]
	v_mfma_f32_16x16x32_f16 v[116:119], v[188:191], v[164:167], v[116:119]
	s_waitcnt lgkmcnt(6)
	v_mfma_f32_16x16x32_f16 v[112:115], v[176:179], v[168:171], v[112:115]
	v_mfma_f32_16x16x32_f16 v[108:111], v[180:183], v[168:171], v[108:111]
	v_mfma_f32_16x16x32_f16 v[104:107], v[184:187], v[168:171], v[104:107]
	v_mfma_f32_16x16x32_f16 v[100:103], v[188:191], v[168:171], v[100:103]
	s_waitcnt lgkmcnt(5)
	v_mfma_f32_16x16x32_f16 v[96:99], v[176:179], v[172:175], v[96:99]
	v_mfma_f32_16x16x32_f16 v[92:95], v[180:183], v[172:175], v[92:95]
	v_mfma_f32_16x16x32_f16 v[88:91], v[184:187], v[172:175], v[88:91]
	v_mfma_f32_16x16x32_f16 v[84:87], v[188:191], v[172:175], v[84:87]
	s_waitcnt lgkmcnt(4)
	v_mfma_f32_16x16x32_f16 v[80:83], v[176:179], v[192:195], v[80:83]
	v_mfma_f32_16x16x32_f16 v[76:79], v[180:183], v[192:195], v[76:79]
	v_mfma_f32_16x16x32_f16 v[72:75], v[184:187], v[192:195], v[72:75]
	v_mfma_f32_16x16x32_f16 v[68:71], v[188:191], v[192:195], v[68:71]
	s_setprio 0
	ds_read_b128 v[192:195], v238
	ds_read_b128 v[172:175], v238 offset:256
	ds_read_b128 v[168:171], v238 offset:512
	ds_read_b128 v[164:167], v238 offset:768
	s_setprio 1
	s_waitcnt lgkmcnt(7)
	v_mfma_f32_16x16x32_f16 v[64:67], v[176:179], v[196:199], v[64:67]
	v_mfma_f32_16x16x32_f16 v[60:63], v[180:183], v[196:199], v[60:63]
	v_mfma_f32_16x16x32_f16 v[56:59], v[184:187], v[196:199], v[56:59]
	v_mfma_f32_16x16x32_f16 v[52:55], v[188:191], v[196:199], v[52:55]
	v_add3_u32 v196, v239, v235, v237
	s_waitcnt lgkmcnt(6)
	v_mfma_f32_16x16x32_f16 v[48:51], v[176:179], v[200:203], v[48:51]
	v_mfma_f32_16x16x32_f16 v[44:47], v[180:183], v[200:203], v[44:47]
	v_mfma_f32_16x16x32_f16 v[40:43], v[184:187], v[200:203], v[40:43]
	v_mfma_f32_16x16x32_f16 v[36:39], v[188:191], v[200:203], v[36:39]
	s_waitcnt lgkmcnt(5)
	v_mfma_f32_16x16x32_f16 v[30:33], v[176:179], v[204:207], v[30:33]
	v_mfma_f32_16x16x32_f16 v[26:29], v[180:183], v[204:207], v[26:29]
	v_mfma_f32_16x16x32_f16 v[22:25], v[184:187], v[204:207], v[22:25]
	v_mfma_f32_16x16x32_f16 v[18:21], v[188:191], v[204:207], v[18:21]
	s_waitcnt lgkmcnt(4)
	v_mfma_f32_16x16x32_f16 v[14:17], v[176:179], v[208:211], v[14:17]
	v_mfma_f32_16x16x32_f16 v[10:13], v[180:183], v[208:211], v[10:13]
	v_mfma_f32_16x16x32_f16 v[6:9], v[184:187], v[208:211], v[6:9]
	v_mfma_f32_16x16x32_f16 v[2:5], v[188:191], v[208:211], v[2:5]
	s_setprio 0
	ds_read_b128 v[176:179], v196
	ds_read_b128 v[180:183], v196 offset:256
	ds_read_b128 v[184:187], v196 offset:512
	ds_read_b128 v[188:191], v196 offset:768
	ds_read_b128 v[208:211], v238 offset:1024
	ds_read_b128 v[204:207], v238 offset:1280
	ds_read_b128 v[200:203], v238 offset:1536
	ds_read_b128 v[196:199], v238 offset:1792
	s_add_i32 s47, s46, 1
	s_cmp_ge_i32 s47, s3
	s_cbranch_scc1 .Lg1_cold
	s_xor_b32 s48, s48, 0x800
	s_lshl_b32 s48, s48, 4
	v_add_u32_e32 v254, s48, v229
	v_add_u32_e32 v255, s48, v230
	s_add_i32 s46, s46, 2
	s_cmp_ge_i32 s46, s3
	s_cbranch_scc1 .Lg1_warm
	v_add_u32_e32 v246, v227, v228
	v_add_u32_e32 v247, v227, v231
	v_lshlrev_b32_e32 v246, 1, v246
	v_lshlrev_b32_e32 v247, 1, v247
	v_add_u32_e32 v248, 0x80000, v246
	v_add_u32_e32 v249, 0x100000, v246
	v_add_u32_e32 v250, 0x180000, v246
	v_add_u32_e32 v251, 0x80000, v247
	v_add_u32_e32 v252, 0x100000, v247
	v_add_u32_e32 v253, 0x180000, v247
	s_setprio 1
	s_waitcnt vmcnt(7)
	ds_write_b128 v254, v[124:127]
	global_load_dwordx4 v[124:127], v246, s[30:31] offset:256
	s_waitcnt lgkmcnt(8)
	v_mfma_f32_16x16x32_f16 v[148:151], v[176:179], v[192:195], v[148:151]
	s_waitcnt lgkmcnt(7)
	v_mfma_f32_16x16x32_f16 v[128:131], v[180:183], v[192:195], v[128:131]
	s_waitcnt lgkmcnt(6)
	v_mfma_f32_16x16x32_f16 v[120:123], v[184:187], v[192:195], v[120:123]
	s_waitcnt lgkmcnt(5)
	v_mfma_f32_16x16x32_f16 v[116:119], v[188:191], v[192:195], v[116:119]
	s_waitcnt vmcnt(7)
	ds_write_b128 v254, v[132:135] offset:1024
	global_load_dwordx4 v[132:135], v248, s[30:31] offset:256
	v_mfma_f32_16x16x32_f16 v[112:115], v[176:179], v[172:175], v[112:115]
	v_mfma_f32_16x16x32_f16 v[108:111], v[180:183], v[172:175], v[108:111]
	v_mfma_f32_16x16x32_f16 v[104:107], v[184:187], v[172:175], v[104:107]
	v_mfma_f32_16x16x32_f16 v[100:103], v[188:191], v[172:175], v[100:103]
	s_waitcnt vmcnt(7)
	ds_write_b128 v254, v[136:139] offset:2048
	global_load_dwordx4 v[136:139], v249, s[30:31] offset:256
	v_mfma_f32_16x16x32_f16 v[96:99], v[176:179], v[168:171], v[96:99]
	v_mfma_f32_16x16x32_f16 v[92:95], v[180:183], v[168:171], v[92:95]
	v_mfma_f32_16x16x32_f16 v[88:91], v[184:187], v[168:171], v[88:91]
	v_mfma_f32_16x16x32_f16 v[84:87], v[188:191], v[168:171], v[84:87]
	s_waitcnt vmcnt(7)
	ds_write_b128 v254, v[140:143] offset:3072
	global_load_dwordx4 v[140:143], v250, s[30:31] offset:256
	v_mfma_f32_16x16x32_f16 v[80:83], v[176:179], v[164:167], v[80:83]
	v_mfma_f32_16x16x32_f16 v[76:79], v[180:183], v[164:167], v[76:79]
	v_mfma_f32_16x16x32_f16 v[72:75], v[184:187], v[164:167], v[72:75]
	v_mfma_f32_16x16x32_f16 v[68:71], v[188:191], v[164:167], v[68:71]
	s_waitcnt vmcnt(7)
	ds_write_b128 v255, v[144:147]
	global_load_dwordx4 v[144:147], v247, s[38:39] offset:256
	s_waitcnt lgkmcnt(5)
	v_mfma_f32_16x16x32_f16 v[64:67], v[176:179], v[208:211], v[64:67]
	v_mfma_f32_16x16x32_f16 v[60:63], v[180:183], v[208:211], v[60:63]
	v_mfma_f32_16x16x32_f16 v[56:59], v[184:187], v[208:211], v[56:59]
	v_mfma_f32_16x16x32_f16 v[52:55], v[188:191], v[208:211], v[52:55]
	s_waitcnt vmcnt(7)
	ds_write_b128 v255, v[152:155] offset:1024
	global_load_dwordx4 v[152:155], v251, s[38:39] offset:256
	v_mfma_f32_16x16x32_f16 v[48:51], v[176:179], v[204:207], v[48:51]
	v_mfma_f32_16x16x32_f16 v[44:47], v[180:183], v[204:207], v[44:47]
	v_mfma_f32_16x16x32_f16 v[40:43], v[184:187], v[204:207], v[40:43]
	v_mfma_f32_16x16x32_f16 v[36:39], v[188:191], v[204:207], v[36:39]
	s_waitcnt vmcnt(7)
	ds_write_b128 v255, v[156:159] offset:2048
	global_load_dwordx4 v[156:159], v252, s[38:39] offset:256
	v_mfma_f32_16x16x32_f16 v[30:33], v[176:179], v[200:203], v[30:33]
	v_mfma_f32_16x16x32_f16 v[26:29], v[180:183], v[200:203], v[26:29]
	v_mfma_f32_16x16x32_f16 v[22:25], v[184:187], v[200:203], v[22:25]
	v_mfma_f32_16x16x32_f16 v[18:21], v[188:191], v[200:203], v[18:21]
	s_waitcnt vmcnt(7)
	ds_write_b128 v255, v[160:163] offset:3072
	global_load_dwordx4 v[160:163], v253, s[38:39] offset:256
	v_mfma_f32_16x16x32_f16 v[14:17], v[176:179], v[196:199], v[14:17]
	v_mfma_f32_16x16x32_f16 v[10:13], v[180:183], v[196:199], v[10:13]
	v_mfma_f32_16x16x32_f16 v[6:9], v[184:187], v[196:199], v[6:9]
	v_mfma_f32_16x16x32_f16 v[2:5], v[188:191], v[196:199], v[2:5]
	s_setprio 0
.Lg1_tail:
	s_addk_i32 s45, 0x800
	v_add_u32_e32 v231, 64, v231
	s_cmp_lg_u32 s3, s47
	v_add_u32_e32 v228, 64, v228
	s_waitcnt lgkmcnt(0)
	s_barrier
	s_cbranch_scc0 .LBB0_91
	s_mov_b32 s46, s47
	s_branch .LBB0_85
.Lg1_cold:
	s_setprio 1
	s_waitcnt lgkmcnt(7)
	v_mfma_f32_16x16x32_f16 v[148:151], v[176:179], v[192:195], v[148:151]
	s_waitcnt lgkmcnt(6)
	v_mfma_f32_16x16x32_f16 v[128:131], v[180:183], v[192:195], v[128:131]
	s_waitcnt lgkmcnt(5)
	v_mfma_f32_16x16x32_f16 v[120:123], v[184:187], v[192:195], v[120:123]
	s_waitcnt lgkmcnt(4)
	v_mfma_f32_16x16x32_f16 v[116:119], v[188:191], v[192:195], v[116:119]
	v_mfma_f32_16x16x32_f16 v[112:115], v[176:179], v[172:175], v[112:115]
	v_mfma_f32_16x16x32_f16 v[108:111], v[180:183], v[172:175], v[108:111]
	v_mfma_f32_16x16x32_f16 v[104:107], v[184:187], v[172:175], v[104:107]
	v_mfma_f32_16x16x32_f16 v[100:103], v[188:191], v[172:175], v[100:103]
	v_mfma_f32_16x16x32_f16 v[96:99], v[176:179], v[168:171], v[96:99]
	v_mfma_f32_16x16x32_f16 v[92:95], v[180:183], v[168:171], v[92:95]
	v_mfma_f32_16x16x32_f16 v[88:91], v[184:187], v[168:171], v[88:91]
	v_mfma_f32_16x16x32_f16 v[84:87], v[188:191], v[168:171], v[84:87]
	v_mfma_f32_16x16x32_f16 v[80:83], v[176:179], v[164:167], v[80:83]
	v_mfma_f32_16x16x32_f16 v[76:79], v[180:183], v[164:167], v[76:79]
	v_mfma_f32_16x16x32_f16 v[72:75], v[184:187], v[164:167], v[72:75]
	v_mfma_f32_16x16x32_f16 v[68:71], v[188:191], v[164:167], v[68:71]
	s_setprio 0
	s_setprio 1
	s_waitcnt lgkmcnt(3)
	v_mfma_f32_16x16x32_f16 v[64:67], v[176:179], v[208:211], v[64:67]
	v_mfma_f32_16x16x32_f16 v[60:63], v[180:183], v[208:211], v[60:63]
	v_mfma_f32_16x16x32_f16 v[56:59], v[184:187], v[208:211], v[56:59]
	v_mfma_f32_16x16x32_f16 v[52:55], v[188:191], v[208:211], v[52:55]
	s_waitcnt lgkmcnt(2)
	v_mfma_f32_16x16x32_f16 v[48:51], v[176:179], v[204:207], v[48:51]
	v_mfma_f32_16x16x32_f16 v[44:47], v[180:183], v[204:207], v[44:47]
	v_mfma_f32_16x16x32_f16 v[40:43], v[184:187], v[204:207], v[40:43]
	v_mfma_f32_16x16x32_f16 v[36:39], v[188:191], v[204:207], v[36:39]
	s_waitcnt lgkmcnt(1)
	v_mfma_f32_16x16x32_f16 v[30:33], v[176:179], v[200:203], v[30:33]
	v_mfma_f32_16x16x32_f16 v[26:29], v[180:183], v[200:203], v[26:29]
	v_mfma_f32_16x16x32_f16 v[22:25], v[184:187], v[200:203], v[22:25]
	v_mfma_f32_16x16x32_f16 v[18:21], v[188:191], v[200:203], v[18:21]
	s_waitcnt lgkmcnt(0)
	v_mfma_f32_16x16x32_f16 v[14:17], v[176:179], v[196:199], v[14:17]
	v_mfma_f32_16x16x32_f16 v[10:13], v[180:183], v[196:199], v[10:13]
	v_mfma_f32_16x16x32_f16 v[6:9], v[184:187], v[196:199], v[6:9]
	v_mfma_f32_16x16x32_f16 v[2:5], v[188:191], v[196:199], v[2:5]
	s_setprio 0
	s_branch .Lg1_tail
.Lg1_warm:
	s_waitcnt vmcnt(7)
	ds_write_b128 v254, v[124:127]
	s_waitcnt vmcnt(6)
	ds_write_b128 v254, v[132:135] offset:1024
	s_waitcnt vmcnt(5)
	ds_write_b128 v254, v[136:139] offset:2048
	s_waitcnt vmcnt(4)
	ds_write_b128 v254, v[140:143] offset:3072
	s_waitcnt vmcnt(3)
	ds_write_b128 v255, v[144:147]
	s_waitcnt vmcnt(2)
	ds_write_b128 v255, v[152:155] offset:1024
	s_waitcnt vmcnt(1)
	ds_write_b128 v255, v[156:159] offset:2048
	s_waitcnt vmcnt(0)
	ds_write_b128 v255, v[160:163] offset:3072
	s_setprio 1
	s_waitcnt lgkmcnt(15)
	v_mfma_f32_16x16x32_f16 v[148:151], v[176:179], v[192:195], v[148:151]
	s_waitcnt lgkmcnt(14)
	v_mfma_f32_16x16x32_f16 v[128:131], v[180:183], v[192:195], v[128:131]
	s_waitcnt lgkmcnt(13)
	v_mfma_f32_16x16x32_f16 v[120:123], v[184:187], v[192:195], v[120:123]
	s_waitcnt lgkmcnt(12)
	v_mfma_f32_16x16x32_f16 v[116:119], v[188:191], v[192:195], v[116:119]
	v_mfma_f32_16x16x32_f16 v[112:115], v[176:179], v[172:175], v[112:115]
	v_mfma_f32_16x16x32_f16 v[108:111], v[180:183], v[172:175], v[108:111]
	v_mfma_f32_16x16x32_f16 v[104:107], v[184:187], v[172:175], v[104:107]
	v_mfma_f32_16x16x32_f16 v[100:103], v[188:191], v[172:175], v[100:103]
	v_mfma_f32_16x16x32_f16 v[96:99], v[176:179], v[168:171], v[96:99]
	v_mfma_f32_16x16x32_f16 v[92:95], v[180:183], v[168:171], v[92:95]
	v_mfma_f32_16x16x32_f16 v[88:91], v[184:187], v[168:171], v[88:91]
	v_mfma_f32_16x16x32_f16 v[84:87], v[188:191], v[168:171], v[84:87]
	v_mfma_f32_16x16x32_f16 v[80:83], v[176:179], v[164:167], v[80:83]
	v_mfma_f32_16x16x32_f16 v[76:79], v[180:183], v[164:167], v[76:79]
	v_mfma_f32_16x16x32_f16 v[72:75], v[184:187], v[164:167], v[72:75]
	v_mfma_f32_16x16x32_f16 v[68:71], v[188:191], v[164:167], v[68:71]
	s_setprio 0
	s_setprio 1
	s_waitcnt lgkmcnt(11)
	v_mfma_f32_16x16x32_f16 v[64:67], v[176:179], v[208:211], v[64:67]
	v_mfma_f32_16x16x32_f16 v[60:63], v[180:183], v[208:211], v[60:63]
	v_mfma_f32_16x16x32_f16 v[56:59], v[184:187], v[208:211], v[56:59]
	v_mfma_f32_16x16x32_f16 v[52:55], v[188:191], v[208:211], v[52:55]
	s_waitcnt lgkmcnt(10)
	v_mfma_f32_16x16x32_f16 v[48:51], v[176:179], v[204:207], v[48:51]
	v_mfma_f32_16x16x32_f16 v[44:47], v[180:183], v[204:207], v[44:47]
	v_mfma_f32_16x16x32_f16 v[40:43], v[184:187], v[204:207], v[40:43]
	v_mfma_f32_16x16x32_f16 v[36:39], v[188:191], v[204:207], v[36:39]
	s_waitcnt lgkmcnt(9)
	v_mfma_f32_16x16x32_f16 v[30:33], v[176:179], v[200:203], v[30:33]
	v_mfma_f32_16x16x32_f16 v[26:29], v[180:183], v[200:203], v[26:29]
	v_mfma_f32_16x16x32_f16 v[22:25], v[184:187], v[200:203], v[22:25]
	v_mfma_f32_16x16x32_f16 v[18:21], v[188:191], v[200:203], v[18:21]
	s_waitcnt lgkmcnt(8)
	v_mfma_f32_16x16x32_f16 v[14:17], v[176:179], v[196:199], v[14:17]
	v_mfma_f32_16x16x32_f16 v[10:13], v[180:183], v[196:199], v[10:13]
	v_mfma_f32_16x16x32_f16 v[6:9], v[184:187], v[196:199], v[6:9]
	v_mfma_f32_16x16x32_f16 v[2:5], v[188:191], v[196:199], v[2:5]
	s_setprio 0
	s_branch .Lg1_tail

.LBB0_132:
	v_mov_b32_e32 v15, v1
	s_ashr_i32 s3, s2, 31
	v_ashrrev_i32_e32 v3, 3, v15
	v_and_b32_e32 v4, 7, v15
	v_lshlrev_b32_e32 v2, 1, v3
	s_lshl_b64 s[30:31], s[2:3], 19
	v_lshlrev_b32_e32 v227, 3, v4
	v_and_b32_e32 v14, 24, v2
	v_lshrrev_b32_e32 v2, 2, v3
	v_lshlrev_b32_e32 v228, 10, v3
	s_add_u32 s30, s16, s30
	v_and_b32_e32 v16, 4, v2
	v_and_b32_e32 v17, 35, v3
	v_or_b32_e32 v2, v228, v227
	v_bitop3_b32 v3, v3, v15, 7 bitop3:0x78
	s_addc_u32 s31, s17, s31
	v_or3_b32 v5, v17, v14, v16
	v_lshl_add_u32 v9, v4, 8, v3
	v_mov_b32_e32 v3, v34
	v_add_u32_e32 v6, 0x10000, v2
	v_mov_b32_e32 v7, v34
	v_lshl_or_b32 v8, v5, 10, v227
	s_mov_b32 s3, 16
	v_lshl_add_u64 v[4:5], v[2:3], 1, s[30:31]
	v_lshl_add_u64 v[6:7], v[6:7], 1, s[30:31]
	global_load_dwordx4 v[116:119], v[4:5], off
	global_load_dwordx4 v[120:123], v[6:7], off
	v_add_u32_e32 v6, 0x20000, v2
	v_mov_b32_e32 v7, v34
	v_lshl_add_u64 v[6:7], v[6:7], 1, s[30:31]
	s_ashr_i32 s23, s22, 31
	global_load_dwordx4 v[128:131], v[6:7], off
	v_add_u32_e32 v6, 0x30000, v2
	v_mov_b32_e32 v7, v34
	s_lshl_b64 s[38:39], s[22:23], 19
	v_lshl_add_u64 v[6:7], v[6:7], 1, s[30:31]
	s_add_u32 s38, s24, s38
	global_load_dwordx4 v[136:139], v[6:7], off
	v_lshlrev_b32_e32 v6, 1, v8
	s_addc_u32 s39, s40, s39
	v_or_b32_e32 v8, 0x20000, v6
	v_or_b32_e32 v10, 0x40000, v6
	v_or_b32_e32 v12, 0x60000, v6
	global_load_dwordx4 v[140:143], v6, s[38:39]
	global_load_dwordx4 v[144:147], v8, s[38:39]
	global_load_dwordx4 v[152:155], v10, s[38:39]
	global_load_dwordx4 v[160:163], v12, s[38:39]
	v_lshl_add_u32 v229, v9, 4, 0
	v_add_u32_e32 v230, 0x10000, v229
	s_cmp_lt_i32 s3, 2
	s_waitcnt vmcnt(7)
	ds_write_b128 v229, v[116:119]
	s_waitcnt vmcnt(6)
	ds_write_b128 v229, v[120:123] offset:1024
	s_waitcnt vmcnt(5)
	ds_write_b128 v229, v[128:131] offset:2048
	s_waitcnt vmcnt(4)
	ds_write_b128 v229, v[136:139] offset:3072
	s_waitcnt vmcnt(3)
	ds_write_b128 v230, v[140:143]
	s_waitcnt vmcnt(2)
	ds_write_b128 v230, v[144:147] offset:1024
	s_waitcnt vmcnt(1)
	ds_write_b128 v230, v[152:155] offset:2048
	s_waitcnt vmcnt(0)
	ds_write_b128 v230, v[160:163] offset:3072
	s_cbranch_scc1 .LBB0_134
	v_add_u32_e32 v20, 0x20040, v2
	v_mov_b32_e32 v21, v34
	v_mov_b32_e32 v7, v34
	v_mov_b32_e32 v9, v34
	v_mov_b32_e32 v11, v34
	v_mov_b32_e32 v13, v34
	v_add_u32_e32 v18, 0x10040, v2
	v_mov_b32_e32 v19, v34
	v_lshl_add_u64 v[20:21], v[20:21], 1, s[30:31]
	v_add_u32_e32 v2, 0x30040, v2
	v_mov_b32_e32 v3, v34
	v_lshl_add_u64 v[6:7], s[38:39], 0, v[6:7]
	v_lshl_add_u64 v[8:9], s[38:39], 0, v[8:9]
	v_lshl_add_u64 v[10:11], s[38:39], 0, v[10:11]
	v_lshl_add_u64 v[12:13], s[38:39], 0, v[12:13]
	v_lshl_add_u64 v[18:19], v[18:19], 1, s[30:31]
	v_lshl_add_u64 v[2:3], v[2:3], 1, s[30:31]
	global_load_dwordx4 v[116:119], v[4:5], off offset:128
	global_load_dwordx4 v[120:123], v[18:19], off
	global_load_dwordx4 v[128:131], v[20:21], off
	global_load_dwordx4 v[136:139], v[2:3], off
	global_load_dwordx4 v[140:143], v[6:7], off offset:128
	global_load_dwordx4 v[144:147], v[8:9], off offset:128
	global_load_dwordx4 v[152:155], v[10:11], off offset:128
	global_load_dwordx4 v[160:163], v[12:13], off offset:128

.LBB0_136:
	s_and_b32 s44, s23, 0x800
	s_lshl_b32 s43, s44, 4
	s_add_i32 s43, s43, 0
	s_add_i32 s45, s43, 0x10000
	v_add_u32_e32 v164, s43, v232
	v_add_u32_e32 v165, s45, v232
	v_add3_u32 v165, v165, v235, v236
	v_add3_u32 v208, v164, v233, v236
	ds_read_b128 v[176:179], v165
	ds_read_b128 v[180:183], v165 offset:256
	ds_read_b128 v[184:187], v165 offset:512
	ds_read_b128 v[188:191], v165 offset:768
	ds_read_b128 v[164:167], v208
	ds_read_b128 v[168:171], v208 offset:256
	ds_read_b128 v[172:175], v208 offset:512
	ds_read_b128 v[192:195], v208 offset:768
	ds_read_b128 v[196:199], v208 offset:1024
	ds_read_b128 v[200:203], v208 offset:1280
	ds_read_b128 v[204:207], v208 offset:1536
	ds_read_b128 v[208:211], v208 offset:1792
	v_add_u32_e32 v238, s43, v234
	v_add_u32_e32 v239, s45, v234
	v_add3_u32 v238, v238, v233, v237
	s_setprio 1
	s_waitcnt lgkmcnt(7)
	v_mfma_f32_16x16x32_f16 v[156:159], v[176:179], v[164:167], v[156:159]
	v_mfma_f32_16x16x32_f16 v[148:151], v[180:183], v[164:167], v[148:151]
	v_mfma_f32_16x16x32_f16 v[132:135], v[184:187], v[164:167], v[132:135]
	v_mfma_f32_16x16x32_f16 v[124:127], v[188:191], v[164:167], v[124:127]
	s_waitcnt lgkmcnt(6)
	v_mfma_f32_16x16x32_f16 v[112:115], v[176:179], v[168:171], v[112:115]
	v_mfma_f32_16x16x32_f16 v[108:111], v[180:183], v[168:171], v[108:111]
	v_mfma_f32_16x16x32_f16 v[104:107], v[184:187], v[168:171], v[104:107]
	v_mfma_f32_16x16x32_f16 v[100:103], v[188:191], v[168:171], v[100:103]
	s_waitcnt lgkmcnt(5)
	v_mfma_f32_16x16x32_f16 v[96:99], v[176:179], v[172:175], v[96:99]
	v_mfma_f32_16x16x32_f16 v[92:95], v[180:183], v[172:175], v[92:95]
	v_mfma_f32_16x16x32_f16 v[88:91], v[184:187], v[172:175], v[88:91]
	v_mfma_f32_16x16x32_f16 v[84:87], v[188:191], v[172:175], v[84:87]
	s_waitcnt lgkmcnt(4)
	v_mfma_f32_16x16x32_f16 v[80:83], v[176:179], v[192:195], v[80:83]
	v_mfma_f32_16x16x32_f16 v[76:79], v[180:183], v[192:195], v[76:79]
	v_mfma_f32_16x16x32_f16 v[72:75], v[184:187], v[192:195], v[72:75]
	v_mfma_f32_16x16x32_f16 v[68:71], v[188:191], v[192:195], v[68:71]
	s_setprio 0
	ds_read_b128 v[192:195], v238
	ds_read_b128 v[172:175], v238 offset:256
	ds_read_b128 v[168:171], v238 offset:512
	ds_read_b128 v[164:167], v238 offset:768
	s_setprio 1
	s_waitcnt lgkmcnt(7)
	v_mfma_f32_16x16x32_f16 v[64:67], v[176:179], v[196:199], v[64:67]
	v_mfma_f32_16x16x32_f16 v[60:63], v[180:183], v[196:199], v[60:63]
	v_mfma_f32_16x16x32_f16 v[56:59], v[184:187], v[196:199], v[56:59]
	v_mfma_f32_16x16x32_f16 v[52:55], v[188:191], v[196:199], v[52:55]
	v_add3_u32 v196, v239, v235, v237
	s_waitcnt lgkmcnt(6)
	v_mfma_f32_16x16x32_f16 v[48:51], v[176:179], v[200:203], v[48:51]
	v_mfma_f32_16x16x32_f16 v[44:47], v[180:183], v[200:203], v[44:47]
	v_mfma_f32_16x16x32_f16 v[40:43], v[184:187], v[200:203], v[40:43]
	v_mfma_f32_16x16x32_f16 v[36:39], v[188:191], v[200:203], v[36:39]
	s_waitcnt lgkmcnt(5)
	v_mfma_f32_16x16x32_f16 v[30:33], v[176:179], v[204:207], v[30:33]
	v_mfma_f32_16x16x32_f16 v[26:29], v[180:183], v[204:207], v[26:29]
	v_mfma_f32_16x16x32_f16 v[22:25], v[184:187], v[204:207], v[22:25]
	v_mfma_f32_16x16x32_f16 v[18:21], v[188:191], v[204:207], v[18:21]
	s_waitcnt lgkmcnt(4)
	v_mfma_f32_16x16x32_f16 v[14:17], v[176:179], v[208:211], v[14:17]
	v_mfma_f32_16x16x32_f16 v[10:13], v[180:183], v[208:211], v[10:13]
	v_mfma_f32_16x16x32_f16 v[6:9], v[184:187], v[208:211], v[6:9]
	v_mfma_f32_16x16x32_f16 v[2:5], v[188:191], v[208:211], v[2:5]
	s_setprio 0
	ds_read_b128 v[176:179], v196
	ds_read_b128 v[180:183], v196 offset:256
	ds_read_b128 v[184:187], v196 offset:512
	ds_read_b128 v[188:191], v196 offset:768
	ds_read_b128 v[208:211], v238 offset:1024
	ds_read_b128 v[204:207], v238 offset:1280
	ds_read_b128 v[200:203], v238 offset:1536
	ds_read_b128 v[196:199], v238 offset:1792
	s_add_i32 s43, s42, 1
	s_cmp_ge_i32 s43, s3
	s_cbranch_scc1 .Lg2_cold
	s_xor_b32 s44, s44, 0x800
	s_lshl_b32 s44, s44, 4
	v_add_u32_e32 v254, s44, v229
	v_add_u32_e32 v255, s44, v230
	s_add_i32 s42, s42, 2
	s_cmp_ge_i32 s42, s3
	s_cbranch_scc1 .Lg2_warm
	v_add_u32_e32 v246, v227, v228
	v_add_u32_e32 v247, v227, v231
	v_lshlrev_b32_e32 v246, 1, v246
	v_lshlrev_b32_e32 v247, 1, v247
	v_add_u32_e32 v248, 0x20000, v246
	v_add_u32_e32 v249, 0x40000, v246
	v_add_u32_e32 v250, 0x60000, v246
	v_add_u32_e32 v251, 0x20000, v247
	v_add_u32_e32 v252, 0x40000, v247
	v_add_u32_e32 v253, 0x60000, v247
	s_setprio 1
	s_waitcnt vmcnt(7)
	ds_write_b128 v254, v[116:119]
	global_load_dwordx4 v[116:119], v246, s[30:31] offset:256
	s_waitcnt lgkmcnt(8)
	v_mfma_f32_16x16x32_f16 v[156:159], v[176:179], v[192:195], v[156:159]
	s_waitcnt lgkmcnt(7)
	v_mfma_f32_16x16x32_f16 v[148:151], v[180:183], v[192:195], v[148:151]
	s_waitcnt lgkmcnt(6)
	v_mfma_f32_16x16x32_f16 v[132:135], v[184:187], v[192:195], v[132:135]
	s_waitcnt lgkmcnt(5)
	v_mfma_f32_16x16x32_f16 v[124:127], v[188:191], v[192:195], v[124:127]
	s_waitcnt vmcnt(7)
	ds_write_b128 v254, v[120:123] offset:1024
	global_load_dwordx4 v[120:123], v248, s[30:31] offset:256
	v_mfma_f32_16x16x32_f16 v[112:115], v[176:179], v[172:175], v[112:115]
	v_mfma_f32_16x16x32_f16 v[108:111], v[180:183], v[172:175], v[108:111]
	v_mfma_f32_16x16x32_f16 v[104:107], v[184:187], v[172:175], v[104:107]
	v_mfma_f32_16x16x32_f16 v[100:103], v[188:191], v[172:175], v[100:103]
	s_waitcnt vmcnt(7)
	ds_write_b128 v254, v[128:131] offset:2048
	global_load_dwordx4 v[128:131], v249, s[30:31] offset:256
	v_mfma_f32_16x16x32_f16 v[96:99], v[176:179], v[168:171], v[96:99]
	v_mfma_f32_16x16x32_f16 v[92:95], v[180:183], v[168:171], v[92:95]
	v_mfma_f32_16x16x32_f16 v[88:91], v[184:187], v[168:171], v[88:91]
	v_mfma_f32_16x16x32_f16 v[84:87], v[188:191], v[168:171], v[84:87]
	s_waitcnt vmcnt(7)
	ds_write_b128 v254, v[136:139] offset:3072
	global_load_dwordx4 v[136:139], v250, s[30:31] offset:256
	v_mfma_f32_16x16x32_f16 v[80:83], v[176:179], v[164:167], v[80:83]
	v_mfma_f32_16x16x32_f16 v[76:79], v[180:183], v[164:167], v[76:79]
	v_mfma_f32_16x16x32_f16 v[72:75], v[184:187], v[164:167], v[72:75]
	v_mfma_f32_16x16x32_f16 v[68:71], v[188:191], v[164:167], v[68:71]
	s_waitcnt vmcnt(7)
	ds_write_b128 v255, v[140:143]
	global_load_dwordx4 v[140:143], v247, s[38:39] offset:256
	s_waitcnt lgkmcnt(5)
	v_mfma_f32_16x16x32_f16 v[64:67], v[176:179], v[208:211], v[64:67]
	v_mfma_f32_16x16x32_f16 v[60:63], v[180:183], v[208:211], v[60:63]
	v_mfma_f32_16x16x32_f16 v[56:59], v[184:187], v[208:211], v[56:59]
	v_mfma_f32_16x16x32_f16 v[52:55], v[188:191], v[208:211], v[52:55]
	s_waitcnt vmcnt(7)
	ds_write_b128 v255, v[144:147] offset:1024
	global_load_dwordx4 v[144:147], v251, s[38:39] offset:256
	v_mfma_f32_16x16x32_f16 v[48:51], v[176:179], v[204:207], v[48:51]
	v_mfma_f32_16x16x32_f16 v[44:47], v[180:183], v[204:207], v[44:47]
	v_mfma_f32_16x16x32_f16 v[40:43], v[184:187], v[204:207], v[40:43]
	v_mfma_f32_16x16x32_f16 v[36:39], v[188:191], v[204:207], v[36:39]
	s_waitcnt vmcnt(7)
	ds_write_b128 v255, v[152:155] offset:2048
	global_load_dwordx4 v[152:155], v252, s[38:39] offset:256
	v_mfma_f32_16x16x32_f16 v[30:33], v[176:179], v[200:203], v[30:33]
	v_mfma_f32_16x16x32_f16 v[26:29], v[180:183], v[200:203], v[26:29]
	v_mfma_f32_16x16x32_f16 v[22:25], v[184:187], v[200:203], v[22:25]
	v_mfma_f32_16x16x32_f16 v[18:21], v[188:191], v[200:203], v[18:21]
	s_waitcnt vmcnt(7)
	ds_write_b128 v255, v[160:163] offset:3072
	global_load_dwordx4 v[160:163], v253, s[38:39] offset:256
	v_mfma_f32_16x16x32_f16 v[14:17], v[176:179], v[196:199], v[14:17]
	v_mfma_f32_16x16x32_f16 v[10:13], v[180:183], v[196:199], v[10:13]
	v_mfma_f32_16x16x32_f16 v[6:9], v[184:187], v[196:199], v[6:9]
	v_mfma_f32_16x16x32_f16 v[2:5], v[188:191], v[196:199], v[2:5]
	s_setprio 0
.Lg2_tail:
	s_addk_i32 s23, 0x800
	v_add_u32_e32 v231, 64, v231
	s_cmp_lg_u32 s3, s43
	v_add_u32_e32 v228, 64, v228
	s_waitcnt lgkmcnt(0)
	s_barrier
	s_cbranch_scc0 .LBB0_142
	s_mov_b32 s42, s43
	s_branch .LBB0_136
.Lg2_cold:
	s_setprio 1
	s_waitcnt lgkmcnt(7)
	v_mfma_f32_16x16x32_f16 v[156:159], v[176:179], v[192:195], v[156:159]
	s_waitcnt lgkmcnt(6)
	v_mfma_f32_16x16x32_f16 v[148:151], v[180:183], v[192:195], v[148:151]
	s_waitcnt lgkmcnt(5)
	v_mfma_f32_16x16x32_f16 v[132:135], v[184:187], v[192:195], v[132:135]
	s_waitcnt lgkmcnt(4)
	v_mfma_f32_16x16x32_f16 v[124:127], v[188:191], v[192:195], v[124:127]
	v_mfma_f32_16x16x32_f16 v[112:115], v[176:179], v[172:175], v[112:115]
	v_mfma_f32_16x16x32_f16 v[108:111], v[180:183], v[172:175], v[108:111]
	v_mfma_f32_16x16x32_f16 v[104:107], v[184:187], v[172:175], v[104:107]
	v_mfma_f32_16x16x32_f16 v[100:103], v[188:191], v[172:175], v[100:103]
	v_mfma_f32_16x16x32_f16 v[96:99], v[176:179], v[168:171], v[96:99]
	v_mfma_f32_16x16x32_f16 v[92:95], v[180:183], v[168:171], v[92:95]
	v_mfma_f32_16x16x32_f16 v[88:91], v[184:187], v[168:171], v[88:91]
	v_mfma_f32_16x16x32_f16 v[84:87], v[188:191], v[168:171], v[84:87]
	v_mfma_f32_16x16x32_f16 v[80:83], v[176:179], v[164:167], v[80:83]
	v_mfma_f32_16x16x32_f16 v[76:79], v[180:183], v[164:167], v[76:79]
	v_mfma_f32_16x16x32_f16 v[72:75], v[184:187], v[164:167], v[72:75]
	v_mfma_f32_16x16x32_f16 v[68:71], v[188:191], v[164:167], v[68:71]
	s_setprio 0
	s_setprio 1
	s_waitcnt lgkmcnt(3)
	v_mfma_f32_16x16x32_f16 v[64:67], v[176:179], v[208:211], v[64:67]
	v_mfma_f32_16x16x32_f16 v[60:63], v[180:183], v[208:211], v[60:63]
	v_mfma_f32_16x16x32_f16 v[56:59], v[184:187], v[208:211], v[56:59]
	v_mfma_f32_16x16x32_f16 v[52:55], v[188:191], v[208:211], v[52:55]
	s_waitcnt lgkmcnt(2)
	v_mfma_f32_16x16x32_f16 v[48:51], v[176:179], v[204:207], v[48:51]
	v_mfma_f32_16x16x32_f16 v[44:47], v[180:183], v[204:207], v[44:47]
	v_mfma_f32_16x16x32_f16 v[40:43], v[184:187], v[204:207], v[40:43]
	v_mfma_f32_16x16x32_f16 v[36:39], v[188:191], v[204:207], v[36:39]
	s_waitcnt lgkmcnt(1)
	v_mfma_f32_16x16x32_f16 v[30:33], v[176:179], v[200:203], v[30:33]
	v_mfma_f32_16x16x32_f16 v[26:29], v[180:183], v[200:203], v[26:29]
	v_mfma_f32_16x16x32_f16 v[22:25], v[184:187], v[200:203], v[22:25]
	v_mfma_f32_16x16x32_f16 v[18:21], v[188:191], v[200:203], v[18:21]
	s_waitcnt lgkmcnt(0)
	v_mfma_f32_16x16x32_f16 v[14:17], v[176:179], v[196:199], v[14:17]
	v_mfma_f32_16x16x32_f16 v[10:13], v[180:183], v[196:199], v[10:13]
	v_mfma_f32_16x16x32_f16 v[6:9], v[184:187], v[196:199], v[6:9]
	v_mfma_f32_16x16x32_f16 v[2:5], v[188:191], v[196:199], v[2:5]
	s_setprio 0
	s_branch .Lg2_tail
.Lg2_warm:
	s_waitcnt vmcnt(7)
	ds_write_b128 v254, v[116:119]
	s_waitcnt vmcnt(6)
	ds_write_b128 v254, v[120:123] offset:1024
	s_waitcnt vmcnt(5)
	ds_write_b128 v254, v[128:131] offset:2048
	s_waitcnt vmcnt(4)
	ds_write_b128 v254, v[136:139] offset:3072
	s_waitcnt vmcnt(3)
	ds_write_b128 v255, v[140:143]
	s_waitcnt vmcnt(2)
	ds_write_b128 v255, v[144:147] offset:1024
	s_waitcnt vmcnt(1)
	ds_write_b128 v255, v[152:155] offset:2048
	s_waitcnt vmcnt(0)
	ds_write_b128 v255, v[160:163] offset:3072
	s_setprio 1
	s_waitcnt lgkmcnt(15)
	v_mfma_f32_16x16x32_f16 v[156:159], v[176:179], v[192:195], v[156:159]
	s_waitcnt lgkmcnt(14)
	v_mfma_f32_16x16x32_f16 v[148:151], v[180:183], v[192:195], v[148:151]
	s_waitcnt lgkmcnt(13)
	v_mfma_f32_16x16x32_f16 v[132:135], v[184:187], v[192:195], v[132:135]
	s_waitcnt lgkmcnt(12)
	v_mfma_f32_16x16x32_f16 v[124:127], v[188:191], v[192:195], v[124:127]
	v_mfma_f32_16x16x32_f16 v[112:115], v[176:179], v[172:175], v[112:115]
	v_mfma_f32_16x16x32_f16 v[108:111], v[180:183], v[172:175], v[108:111]
	v_mfma_f32_16x16x32_f16 v[104:107], v[184:187], v[172:175], v[104:107]
	v_mfma_f32_16x16x32_f16 v[100:103], v[188:191], v[172:175], v[100:103]
	v_mfma_f32_16x16x32_f16 v[96:99], v[176:179], v[168:171], v[96:99]
	v_mfma_f32_16x16x32_f16 v[92:95], v[180:183], v[168:171], v[92:95]
	v_mfma_f32_16x16x32_f16 v[88:91], v[184:187], v[168:171], v[88:91]
	v_mfma_f32_16x16x32_f16 v[84:87], v[188:191], v[168:171], v[84:87]
	v_mfma_f32_16x16x32_f16 v[80:83], v[176:179], v[164:167], v[80:83]
	v_mfma_f32_16x16x32_f16 v[76:79], v[180:183], v[164:167], v[76:79]
	v_mfma_f32_16x16x32_f16 v[72:75], v[184:187], v[164:167], v[72:75]
	v_mfma_f32_16x16x32_f16 v[68:71], v[188:191], v[164:167], v[68:71]
	s_setprio 0
	s_setprio 1
	s_waitcnt lgkmcnt(11)
	v_mfma_f32_16x16x32_f16 v[64:67], v[176:179], v[208:211], v[64:67]
	v_mfma_f32_16x16x32_f16 v[60:63], v[180:183], v[208:211], v[60:63]
	v_mfma_f32_16x16x32_f16 v[56:59], v[184:187], v[208:211], v[56:59]
	v_mfma_f32_16x16x32_f16 v[52:55], v[188:191], v[208:211], v[52:55]
	s_waitcnt lgkmcnt(10)
	v_mfma_f32_16x16x32_f16 v[48:51], v[176:179], v[204:207], v[48:51]
	v_mfma_f32_16x16x32_f16 v[44:47], v[180:183], v[204:207], v[44:47]
	v_mfma_f32_16x16x32_f16 v[40:43], v[184:187], v[204:207], v[40:43]
	v_mfma_f32_16x16x32_f16 v[36:39], v[188:191], v[204:207], v[36:39]
	s_waitcnt lgkmcnt(9)
	v_mfma_f32_16x16x32_f16 v[30:33], v[176:179], v[200:203], v[30:33]
	v_mfma_f32_16x16x32_f16 v[26:29], v[180:183], v[200:203], v[26:29]
	v_mfma_f32_16x16x32_f16 v[22:25], v[184:187], v[200:203], v[22:25]
	v_mfma_f32_16x16x32_f16 v[18:21], v[188:191], v[200:203], v[18:21]
	s_waitcnt lgkmcnt(8)
	v_mfma_f32_16x16x32_f16 v[14:17], v[176:179], v[196:199], v[14:17]
	v_mfma_f32_16x16x32_f16 v[10:13], v[180:183], v[196:199], v[10:13]
	v_mfma_f32_16x16x32_f16 v[6:9], v[184:187], v[196:199], v[6:9]
	v_mfma_f32_16x16x32_f16 v[2:5], v[188:191], v[196:199], v[2:5]
	s_setprio 0
	s_branch .Lg2_tail

.LBB0_189:
	s_mul_i32 s3, s42, s43
	s_mul_hi_u32 s2, s42, s43
	s_add_u32 s30, s3, s37
	s_addc_u32 s31, s2, 0
	s_lshr_b64 s[2:3], s[30:31], 2
	s_and_b32 s2, s2, -8
	s_or_b32 s31, s2, s35
	s_cmp_lt_i32 s31, 16
	s_cselect_b64 s[22:23], -1, 0
	s_cmp_gt_i32 s31, 15
	s_mov_b64 s[38:39], -1
	s_cbranch_scc1 .LBB0_188
	s_lshl_b32 s2, s31, 3
	s_and_b32 s3, s30, 7
	v_mov_b32_e32 v15, v1
	s_or_b32 s2, s2, s3
	s_ashr_i32 s3, s2, 31
	v_ashrrev_i32_e32 v3, 3, v15
	v_and_b32_e32 v4, 7, v15
	v_lshlrev_b32_e32 v2, 1, v3
	s_bfe_u32 s46, s30, 0x20003
	s_lshl_b64 s[30:31], s[2:3], 19
	v_lshlrev_b32_e32 v227, 3, v4
	v_and_b32_e32 v14, 24, v2
	v_lshrrev_b32_e32 v2, 2, v3
	v_lshlrev_b32_e32 v228, 10, v3
	s_add_u32 s30, s40, s30
	v_and_b32_e32 v16, 4, v2
	v_and_b32_e32 v17, 35, v3
	v_or_b32_e32 v2, v228, v227
	v_bitop3_b32 v3, v3, v15, 7 bitop3:0x78
	s_addc_u32 s31, s41, s31
	s_lshl_b32 s3, s46, 19
	v_or3_b32 v5, v17, v14, v16
	v_lshl_add_u32 v9, v4, 8, v3
	v_mov_b32_e32 v3, v34
	v_add_u32_e32 v6, 0x10000, v2
	v_mov_b32_e32 v7, v34
	s_add_u32 s38, s24, s3
	v_lshl_or_b32 v8, v5, 10, v227
	s_mov_b32 s3, 16
	v_lshl_add_u64 v[4:5], v[2:3], 1, s[30:31]
	v_lshl_add_u64 v[6:7], v[6:7], 1, s[30:31]
	global_load_dwordx4 v[124:127], v[4:5], off
	global_load_dwordx4 v[132:135], v[6:7], off
	v_add_u32_e32 v6, 0x20000, v2
	v_mov_b32_e32 v7, v34
	v_lshl_add_u64 v[6:7], v[6:7], 1, s[30:31]
	global_load_dwordx4 v[136:139], v[6:7], off
	v_add_u32_e32 v6, 0x30000, v2
	v_mov_b32_e32 v7, v34
	v_lshl_add_u64 v[6:7], v[6:7], 1, s[30:31]
	global_load_dwordx4 v[140:143], v[6:7], off
	v_lshlrev_b32_e32 v6, 1, v8
	s_addc_u32 s39, s33, 0
	v_or_b32_e32 v8, 0x20000, v6
	v_or_b32_e32 v10, 0x40000, v6
	v_or_b32_e32 v12, 0x60000, v6
	global_load_dwordx4 v[144:147], v6, s[38:39]
	global_load_dwordx4 v[152:155], v8, s[38:39]
	global_load_dwordx4 v[156:159], v10, s[38:39]
	global_load_dwordx4 v[160:163], v12, s[38:39]
	v_lshl_add_u32 v229, v9, 4, 0
	v_add_u32_e32 v230, 0x10000, v229
	s_cmp_lt_i32 s3, 2
	s_waitcnt vmcnt(7)
	ds_write_b128 v229, v[124:127]
	s_waitcnt vmcnt(6)
	ds_write_b128 v229, v[132:135] offset:1024
	s_waitcnt vmcnt(5)
	ds_write_b128 v229, v[136:139] offset:2048
	s_waitcnt vmcnt(4)
	ds_write_b128 v229, v[140:143] offset:3072
	s_waitcnt vmcnt(3)
	ds_write_b128 v230, v[144:147]
	s_waitcnt vmcnt(2)
	ds_write_b128 v230, v[152:155] offset:1024
	s_waitcnt vmcnt(1)
	ds_write_b128 v230, v[156:159] offset:2048
	s_waitcnt vmcnt(0)
	ds_write_b128 v230, v[160:163] offset:3072
	s_cbranch_scc1 .LBB0_192
	v_add_u32_e32 v20, 0x20040, v2
	v_mov_b32_e32 v21, v34
	v_mov_b32_e32 v7, v34
	v_mov_b32_e32 v9, v34
	v_mov_b32_e32 v11, v34
	v_mov_b32_e32 v13, v34
	v_add_u32_e32 v18, 0x10040, v2
	v_mov_b32_e32 v19, v34
	v_lshl_add_u64 v[20:21], v[20:21], 1, s[30:31]
	v_add_u32_e32 v2, 0x30040, v2
	v_mov_b32_e32 v3, v34
	v_lshl_add_u64 v[6:7], s[38:39], 0, v[6:7]
	v_lshl_add_u64 v[8:9], s[38:39], 0, v[8:9]
	v_lshl_add_u64 v[10:11], s[38:39], 0, v[10:11]
	v_lshl_add_u64 v[12:13], s[38:39], 0, v[12:13]
	v_lshl_add_u64 v[18:19], v[18:19], 1, s[30:31]
	v_lshl_add_u64 v[2:3], v[2:3], 1, s[30:31]
	global_load_dwordx4 v[124:127], v[4:5], off offset:128
	global_load_dwordx4 v[132:135], v[18:19], off
	global_load_dwordx4 v[136:139], v[20:21], off
	global_load_dwordx4 v[140:143], v[2:3], off
	global_load_dwordx4 v[144:147], v[6:7], off offset:128
	global_load_dwordx4 v[152:155], v[8:9], off offset:128
	global_load_dwordx4 v[156:159], v[10:11], off offset:128
	global_load_dwordx4 v[160:163], v[12:13], off offset:128

.LBB0_194:
	s_and_b32 s50, s47, 0x800
	s_lshl_b32 s49, s50, 4
	s_add_i32 s49, s49, 0
	s_add_i32 s51, s49, 0x10000
	v_add_u32_e32 v164, s49, v232
	v_add_u32_e32 v165, s51, v232
	v_add3_u32 v165, v165, v235, v236
	v_add3_u32 v208, v164, v233, v236
	ds_read_b128 v[176:179], v165
	ds_read_b128 v[180:183], v165 offset:256
	ds_read_b128 v[184:187], v165 offset:512
	ds_read_b128 v[188:191], v165 offset:768
	ds_read_b128 v[164:167], v208
	ds_read_b128 v[168:171], v208 offset:256
	ds_read_b128 v[172:175], v208 offset:512
	ds_read_b128 v[192:195], v208 offset:768
	ds_read_b128 v[196:199], v208 offset:1024
	ds_read_b128 v[200:203], v208 offset:1280
	ds_read_b128 v[204:207], v208 offset:1536
	ds_read_b128 v[208:211], v208 offset:1792
	v_add_u32_e32 v238, s49, v234
	v_add_u32_e32 v239, s51, v234
	v_add3_u32 v238, v238, v233, v237
	s_setprio 1
	s_waitcnt lgkmcnt(7)
	v_mfma_f32_16x16x32_f16 v[148:151], v[176:179], v[164:167], v[148:151]
	v_mfma_f32_16x16x32_f16 v[128:131], v[180:183], v[164:167], v[128:131]
	v_mfma_f32_16x16x32_f16 v[120:123], v[184:187], v[164:167], v[120:123]
	v_mfma_f32_16x16x32_f16 v[116:119], v[188:191], v[164:167], v[116:119]
	s_waitcnt lgkmcnt(6)
	v_mfma_f32_16x16x32_f16 v[112:115], v[176:179], v[168:171], v[112:115]
	v_mfma_f32_16x16x32_f16 v[108:111], v[180:183], v[168:171], v[108:111]
	v_mfma_f32_16x16x32_f16 v[104:107], v[184:187], v[168:171], v[104:107]
	v_mfma_f32_16x16x32_f16 v[100:103], v[188:191], v[168:171], v[100:103]
	s_waitcnt lgkmcnt(5)
	v_mfma_f32_16x16x32_f16 v[96:99], v[176:179], v[172:175], v[96:99]
	v_mfma_f32_16x16x32_f16 v[92:95], v[180:183], v[172:175], v[92:95]
	v_mfma_f32_16x16x32_f16 v[88:91], v[184:187], v[172:175], v[88:91]
	v_mfma_f32_16x16x32_f16 v[84:87], v[188:191], v[172:175], v[84:87]
	s_waitcnt lgkmcnt(4)
	v_mfma_f32_16x16x32_f16 v[80:83], v[176:179], v[192:195], v[80:83]
	v_mfma_f32_16x16x32_f16 v[76:79], v[180:183], v[192:195], v[76:79]
	v_mfma_f32_16x16x32_f16 v[72:75], v[184:187], v[192:195], v[72:75]
	v_mfma_f32_16x16x32_f16 v[68:71], v[188:191], v[192:195], v[68:71]
	s_setprio 0
	ds_read_b128 v[192:195], v238
	ds_read_b128 v[172:175], v238 offset:256
	ds_read_b128 v[168:171], v238 offset:512
	ds_read_b128 v[164:167], v238 offset:768
	s_setprio 1
	s_waitcnt lgkmcnt(7)
	v_mfma_f32_16x16x32_f16 v[64:67], v[176:179], v[196:199], v[64:67]
	v_mfma_f32_16x16x32_f16 v[60:63], v[180:183], v[196:199], v[60:63]
	v_mfma_f32_16x16x32_f16 v[56:59], v[184:187], v[196:199], v[56:59]
	v_mfma_f32_16x16x32_f16 v[52:55], v[188:191], v[196:199], v[52:55]
	v_add3_u32 v196, v239, v235, v237
	s_waitcnt lgkmcnt(6)
	v_mfma_f32_16x16x32_f16 v[48:51], v[176:179], v[200:203], v[48:51]
	v_mfma_f32_16x16x32_f16 v[44:47], v[180:183], v[200:203], v[44:47]
	v_mfma_f32_16x16x32_f16 v[40:43], v[184:187], v[200:203], v[40:43]
	v_mfma_f32_16x16x32_f16 v[36:39], v[188:191], v[200:203], v[36:39]
	s_waitcnt lgkmcnt(5)
	v_mfma_f32_16x16x32_f16 v[30:33], v[176:179], v[204:207], v[30:33]
	v_mfma_f32_16x16x32_f16 v[26:29], v[180:183], v[204:207], v[26:29]
	v_mfma_f32_16x16x32_f16 v[22:25], v[184:187], v[204:207], v[22:25]
	v_mfma_f32_16x16x32_f16 v[18:21], v[188:191], v[204:207], v[18:21]
	s_waitcnt lgkmcnt(4)
	v_mfma_f32_16x16x32_f16 v[14:17], v[176:179], v[208:211], v[14:17]
	v_mfma_f32_16x16x32_f16 v[10:13], v[180:183], v[208:211], v[10:13]
	v_mfma_f32_16x16x32_f16 v[6:9], v[184:187], v[208:211], v[6:9]
	v_mfma_f32_16x16x32_f16 v[2:5], v[188:191], v[208:211], v[2:5]
	s_setprio 0
	ds_read_b128 v[176:179], v196
	ds_read_b128 v[180:183], v196 offset:256
	ds_read_b128 v[184:187], v196 offset:512
	ds_read_b128 v[188:191], v196 offset:768
	ds_read_b128 v[208:211], v238 offset:1024
	ds_read_b128 v[204:207], v238 offset:1280
	ds_read_b128 v[200:203], v238 offset:1536
	ds_read_b128 v[196:199], v238 offset:1792
	s_add_i32 s49, s48, 1
	s_cmp_ge_i32 s49, s3
	s_cbranch_scc1 .Lg3_cold
	s_xor_b32 s50, s50, 0x800
	s_lshl_b32 s50, s50, 4
	v_add_u32_e32 v254, s50, v229
	v_add_u32_e32 v255, s50, v230
	s_add_i32 s48, s48, 2
	s_cmp_ge_i32 s48, s3
	s_cbranch_scc1 .Lg3_warm
	v_add_u32_e32 v246, v227, v228
	v_add_u32_e32 v247, v227, v231
	v_lshlrev_b32_e32 v246, 1, v246
	v_lshlrev_b32_e32 v247, 1, v247
	v_add_u32_e32 v248, 0x20000, v246
	v_add_u32_e32 v249, 0x40000, v246
	v_add_u32_e32 v250, 0x60000, v246
	v_add_u32_e32 v251, 0x20000, v247
	v_add_u32_e32 v252, 0x40000, v247
	v_add_u32_e32 v253, 0x60000, v247
	s_setprio 1
	s_waitcnt vmcnt(7)
	ds_write_b128 v254, v[124:127]
	global_load_dwordx4 v[124:127], v246, s[30:31] offset:256
	s_waitcnt lgkmcnt(8)
	v_mfma_f32_16x16x32_f16 v[148:151], v[176:179], v[192:195], v[148:151]
	s_waitcnt lgkmcnt(7)
	v_mfma_f32_16x16x32_f16 v[128:131], v[180:183], v[192:195], v[128:131]
	s_waitcnt lgkmcnt(6)
	v_mfma_f32_16x16x32_f16 v[120:123], v[184:187], v[192:195], v[120:123]
	s_waitcnt lgkmcnt(5)
	v_mfma_f32_16x16x32_f16 v[116:119], v[188:191], v[192:195], v[116:119]
	s_waitcnt vmcnt(7)
	ds_write_b128 v254, v[132:135] offset:1024
	global_load_dwordx4 v[132:135], v248, s[30:31] offset:256
	v_mfma_f32_16x16x32_f16 v[112:115], v[176:179], v[172:175], v[112:115]
	v_mfma_f32_16x16x32_f16 v[108:111], v[180:183], v[172:175], v[108:111]
	v_mfma_f32_16x16x32_f16 v[104:107], v[184:187], v[172:175], v[104:107]
	v_mfma_f32_16x16x32_f16 v[100:103], v[188:191], v[172:175], v[100:103]
	s_waitcnt vmcnt(7)
	ds_write_b128 v254, v[136:139] offset:2048
	global_load_dwordx4 v[136:139], v249, s[30:31] offset:256
	v_mfma_f32_16x16x32_f16 v[96:99], v[176:179], v[168:171], v[96:99]
	v_mfma_f32_16x16x32_f16 v[92:95], v[180:183], v[168:171], v[92:95]
	v_mfma_f32_16x16x32_f16 v[88:91], v[184:187], v[168:171], v[88:91]
	v_mfma_f32_16x16x32_f16 v[84:87], v[188:191], v[168:171], v[84:87]
	s_waitcnt vmcnt(7)
	ds_write_b128 v254, v[140:143] offset:3072
	global_load_dwordx4 v[140:143], v250, s[30:31] offset:256
	v_mfma_f32_16x16x32_f16 v[80:83], v[176:179], v[164:167], v[80:83]
	v_mfma_f32_16x16x32_f16 v[76:79], v[180:183], v[164:167], v[76:79]
	v_mfma_f32_16x16x32_f16 v[72:75], v[184:187], v[164:167], v[72:75]
	v_mfma_f32_16x16x32_f16 v[68:71], v[188:191], v[164:167], v[68:71]
	s_waitcnt vmcnt(7)
	ds_write_b128 v255, v[144:147]
	global_load_dwordx4 v[144:147], v247, s[38:39] offset:256
	s_waitcnt lgkmcnt(5)
	v_mfma_f32_16x16x32_f16 v[64:67], v[176:179], v[208:211], v[64:67]
	v_mfma_f32_16x16x32_f16 v[60:63], v[180:183], v[208:211], v[60:63]
	v_mfma_f32_16x16x32_f16 v[56:59], v[184:187], v[208:211], v[56:59]
	v_mfma_f32_16x16x32_f16 v[52:55], v[188:191], v[208:211], v[52:55]
	s_waitcnt vmcnt(7)
	ds_write_b128 v255, v[152:155] offset:1024
	global_load_dwordx4 v[152:155], v251, s[38:39] offset:256
	v_mfma_f32_16x16x32_f16 v[48:51], v[176:179], v[204:207], v[48:51]
	v_mfma_f32_16x16x32_f16 v[44:47], v[180:183], v[204:207], v[44:47]
	v_mfma_f32_16x16x32_f16 v[40:43], v[184:187], v[204:207], v[40:43]
	v_mfma_f32_16x16x32_f16 v[36:39], v[188:191], v[204:207], v[36:39]
	s_waitcnt vmcnt(7)
	ds_write_b128 v255, v[156:159] offset:2048
	global_load_dwordx4 v[156:159], v252, s[38:39] offset:256
	v_mfma_f32_16x16x32_f16 v[30:33], v[176:179], v[200:203], v[30:33]
	v_mfma_f32_16x16x32_f16 v[26:29], v[180:183], v[200:203], v[26:29]
	v_mfma_f32_16x16x32_f16 v[22:25], v[184:187], v[200:203], v[22:25]
	v_mfma_f32_16x16x32_f16 v[18:21], v[188:191], v[200:203], v[18:21]
	s_waitcnt vmcnt(7)
	ds_write_b128 v255, v[160:163] offset:3072
	global_load_dwordx4 v[160:163], v253, s[38:39] offset:256
	v_mfma_f32_16x16x32_f16 v[14:17], v[176:179], v[196:199], v[14:17]
	v_mfma_f32_16x16x32_f16 v[10:13], v[180:183], v[196:199], v[10:13]
	v_mfma_f32_16x16x32_f16 v[6:9], v[184:187], v[196:199], v[6:9]
	v_mfma_f32_16x16x32_f16 v[2:5], v[188:191], v[196:199], v[2:5]
	s_setprio 0
.Lg3_tail:
	s_addk_i32 s47, 0x800
	v_add_u32_e32 v231, 64, v231
	s_cmp_lg_u32 s3, s49
	v_add_u32_e32 v228, 64, v228
	s_waitcnt lgkmcnt(0)
	s_barrier
	s_cbranch_scc0 .LBB0_200
	s_mov_b32 s48, s49
	s_branch .LBB0_194

.LBB0_802:
	v_mov_b32_e32 v15, v1
	s_load_dwordx2 s[38:39], s[0:1], 0xf8
	s_ashr_i32 s3, s2, 31
	v_ashrrev_i32_e32 v3, 3, v15
	v_and_b32_e32 v4, 7, v15
	v_lshlrev_b32_e32 v2, 1, v3
	s_lshl_b64 s[28:29], s[2:3], 19
	v_lshlrev_b32_e32 v227, 3, v4
	v_and_b32_e32 v14, 24, v2
	v_lshrrev_b32_e32 v2, 2, v3
	v_lshlrev_b32_e32 v228, 10, v3
	s_add_u32 s28, s16, s28
	v_and_b32_e32 v16, 4, v2
	v_and_b32_e32 v17, 35, v3
	v_or_b32_e32 v2, v228, v227
	v_bitop3_b32 v3, v3, v15, 7 bitop3:0x78
	s_addc_u32 s29, s17, s29
	v_or3_b32 v5, v17, v14, v16
	v_lshl_add_u32 v9, v4, 8, v3
	v_mov_b32_e32 v3, v34
	v_add_u32_e32 v6, 0x10000, v2
	v_mov_b32_e32 v7, v34
	v_lshl_or_b32 v8, v5, 10, v227
	s_mov_b32 s3, 16
	v_lshl_add_u64 v[4:5], v[2:3], 1, s[28:29]
	v_lshl_add_u64 v[6:7], v[6:7], 1, s[28:29]
	global_load_dwordx4 v[100:103], v[4:5], off
	global_load_dwordx4 v[108:111], v[6:7], off
	v_add_u32_e32 v6, 0x20000, v2
	v_mov_b32_e32 v7, v34
	v_lshl_add_u64 v[6:7], v[6:7], 1, s[28:29]
	s_ashr_i32 s23, s22, 31
	global_load_dwordx4 v[116:119], v[6:7], off
	v_add_u32_e32 v6, 0x30000, v2
	v_mov_b32_e32 v7, v34
	s_lshl_b64 s[30:31], s[22:23], 19
	v_lshl_add_u64 v[6:7], v[6:7], 1, s[28:29]
	s_waitcnt lgkmcnt(0)
	s_add_u32 s30, s38, s30
	global_load_dwordx4 v[124:127], v[6:7], off
	v_lshlrev_b32_e32 v6, 1, v8
	s_addc_u32 s31, s39, s31
	v_or_b32_e32 v8, 0x20000, v6
	v_or_b32_e32 v10, 0x40000, v6
	v_or_b32_e32 v12, 0x60000, v6
	global_load_dwordx4 v[132:135], v6, s[30:31]
	global_load_dwordx4 v[144:147], v8, s[30:31]
	global_load_dwordx4 v[148:151], v10, s[30:31]
	global_load_dwordx4 v[160:163], v12, s[30:31]
	v_lshl_add_u32 v229, v9, 4, 0
	v_add_u32_e32 v230, 0x10000, v229
	s_cmp_lt_i32 s3, 2
	s_waitcnt vmcnt(7)
	ds_write_b128 v229, v[100:103]
	s_waitcnt vmcnt(6)
	ds_write_b128 v229, v[108:111] offset:1024
	s_waitcnt vmcnt(5)
	ds_write_b128 v229, v[116:119] offset:2048
	s_waitcnt vmcnt(4)
	ds_write_b128 v229, v[124:127] offset:3072
	s_waitcnt vmcnt(3)
	ds_write_b128 v230, v[132:135]
	s_waitcnt vmcnt(2)
	ds_write_b128 v230, v[144:147] offset:1024
	s_waitcnt vmcnt(1)
	ds_write_b128 v230, v[148:151] offset:2048
	s_waitcnt vmcnt(0)
	ds_write_b128 v230, v[160:163] offset:3072
	s_cbranch_scc1 .LBB0_804
	v_add_u32_e32 v20, 0x20040, v2
	v_mov_b32_e32 v21, v34
	v_mov_b32_e32 v7, v34
	v_mov_b32_e32 v9, v34
	v_mov_b32_e32 v11, v34
	v_mov_b32_e32 v13, v34
	v_add_u32_e32 v18, 0x10040, v2
	v_mov_b32_e32 v19, v34
	v_lshl_add_u64 v[20:21], v[20:21], 1, s[28:29]
	v_add_u32_e32 v2, 0x30040, v2
	v_mov_b32_e32 v3, v34
	v_lshl_add_u64 v[6:7], s[30:31], 0, v[6:7]
	v_lshl_add_u64 v[8:9], s[30:31], 0, v[8:9]
	v_lshl_add_u64 v[10:11], s[30:31], 0, v[10:11]
	v_lshl_add_u64 v[12:13], s[30:31], 0, v[12:13]
	v_lshl_add_u64 v[18:19], v[18:19], 1, s[28:29]
	v_lshl_add_u64 v[2:3], v[2:3], 1, s[28:29]
	global_load_dwordx4 v[100:103], v[4:5], off offset:128
	global_load_dwordx4 v[108:111], v[18:19], off
	global_load_dwordx4 v[116:119], v[20:21], off
	global_load_dwordx4 v[124:127], v[2:3], off
	global_load_dwordx4 v[132:135], v[6:7], off offset:128
	global_load_dwordx4 v[144:147], v[8:9], off offset:128
	global_load_dwordx4 v[148:151], v[10:11], off offset:128
	global_load_dwordx4 v[160:163], v[12:13], off offset:128

.LBB0_806:
	s_and_b32 s40, s23, 0x800
	s_lshl_b32 s39, s40, 4
	s_add_i32 s39, s39, 0
	s_add_i32 s41, s39, 0x10000
	v_add_u32_e32 v164, s39, v232
	v_add_u32_e32 v165, s41, v232
	v_add3_u32 v165, v165, v235, v236
	v_add3_u32 v208, v164, v233, v236
	ds_read_b128 v[176:179], v165
	ds_read_b128 v[180:183], v165 offset:256
	ds_read_b128 v[184:187], v165 offset:512
	ds_read_b128 v[188:191], v165 offset:768
	ds_read_b128 v[164:167], v208
	ds_read_b128 v[168:171], v208 offset:256
	ds_read_b128 v[172:175], v208 offset:512
	ds_read_b128 v[192:195], v208 offset:768
	ds_read_b128 v[196:199], v208 offset:1024
	ds_read_b128 v[200:203], v208 offset:1280
	ds_read_b128 v[204:207], v208 offset:1536
	ds_read_b128 v[208:211], v208 offset:1792
	v_add_u32_e32 v238, s39, v234
	v_add_u32_e32 v239, s41, v234
	v_add3_u32 v238, v238, v233, v237
	s_setprio 1
	s_waitcnt lgkmcnt(7)
	v_mfma_f32_16x16x32_f16 v[156:159], v[176:179], v[164:167], v[156:159]
	v_mfma_f32_16x16x32_f16 v[152:155], v[180:183], v[164:167], v[152:155]
	v_mfma_f32_16x16x32_f16 v[140:143], v[184:187], v[164:167], v[140:143]
	v_mfma_f32_16x16x32_f16 v[136:139], v[188:191], v[164:167], v[136:139]
	s_waitcnt lgkmcnt(6)
	v_mfma_f32_16x16x32_f16 v[128:131], v[176:179], v[168:171], v[128:131]
	v_mfma_f32_16x16x32_f16 v[120:123], v[180:183], v[168:171], v[120:123]
	v_mfma_f32_16x16x32_f16 v[112:115], v[184:187], v[168:171], v[112:115]
	v_mfma_f32_16x16x32_f16 v[104:107], v[188:191], v[168:171], v[104:107]
	s_waitcnt lgkmcnt(5)
	v_mfma_f32_16x16x32_f16 v[96:99], v[176:179], v[172:175], v[96:99]
	v_mfma_f32_16x16x32_f16 v[92:95], v[180:183], v[172:175], v[92:95]
	v_mfma_f32_16x16x32_f16 v[88:91], v[184:187], v[172:175], v[88:91]
	v_mfma_f32_16x16x32_f16 v[84:87], v[188:191], v[172:175], v[84:87]
	s_waitcnt lgkmcnt(4)
	v_mfma_f32_16x16x32_f16 v[80:83], v[176:179], v[192:195], v[80:83]
	v_mfma_f32_16x16x32_f16 v[76:79], v[180:183], v[192:195], v[76:79]
	v_mfma_f32_16x16x32_f16 v[72:75], v[184:187], v[192:195], v[72:75]
	v_mfma_f32_16x16x32_f16 v[68:71], v[188:191], v[192:195], v[68:71]
	s_setprio 0
	ds_read_b128 v[192:195], v238
	ds_read_b128 v[172:175], v238 offset:256
	ds_read_b128 v[168:171], v238 offset:512
	ds_read_b128 v[164:167], v238 offset:768
	s_setprio 1
	s_waitcnt lgkmcnt(7)
	v_mfma_f32_16x16x32_f16 v[64:67], v[176:179], v[196:199], v[64:67]
	v_mfma_f32_16x16x32_f16 v[60:63], v[180:183], v[196:199], v[60:63]
	v_mfma_f32_16x16x32_f16 v[56:59], v[184:187], v[196:199], v[56:59]
	v_mfma_f32_16x16x32_f16 v[52:55], v[188:191], v[196:199], v[52:55]
	v_add3_u32 v196, v239, v235, v237
	s_waitcnt lgkmcnt(6)
	v_mfma_f32_16x16x32_f16 v[48:51], v[176:179], v[200:203], v[48:51]
	v_mfma_f32_16x16x32_f16 v[44:47], v[180:183], v[200:203], v[44:47]
	v_mfma_f32_16x16x32_f16 v[40:43], v[184:187], v[200:203], v[40:43]
	v_mfma_f32_16x16x32_f16 v[36:39], v[188:191], v[200:203], v[36:39]
	s_waitcnt lgkmcnt(5)
	v_mfma_f32_16x16x32_f16 v[30:33], v[176:179], v[204:207], v[30:33]
	v_mfma_f32_16x16x32_f16 v[26:29], v[180:183], v[204:207], v[26:29]
	v_mfma_f32_16x16x32_f16 v[22:25], v[184:187], v[204:207], v[22:25]
	v_mfma_f32_16x16x32_f16 v[18:21], v[188:191], v[204:207], v[18:21]
	s_waitcnt lgkmcnt(4)
	v_mfma_f32_16x16x32_f16 v[14:17], v[176:179], v[208:211], v[14:17]
	v_mfma_f32_16x16x32_f16 v[10:13], v[180:183], v[208:211], v[10:13]
	v_mfma_f32_16x16x32_f16 v[6:9], v[184:187], v[208:211], v[6:9]
	v_mfma_f32_16x16x32_f16 v[2:5], v[188:191], v[208:211], v[2:5]
	s_setprio 0
	ds_read_b128 v[176:179], v196
	ds_read_b128 v[180:183], v196 offset:256
	ds_read_b128 v[184:187], v196 offset:512
	ds_read_b128 v[188:191], v196 offset:768
	ds_read_b128 v[208:211], v238 offset:1024
	ds_read_b128 v[204:207], v238 offset:1280
	ds_read_b128 v[200:203], v238 offset:1536
	ds_read_b128 v[196:199], v238 offset:1792
	s_add_i32 s39, s38, 1
	s_cmp_ge_i32 s39, s3
	s_cbranch_scc1 .Lg4_cold
	s_xor_b32 s40, s40, 0x800
	s_lshl_b32 s40, s40, 4
	v_add_u32_e32 v254, s40, v229
	v_add_u32_e32 v255, s40, v230
	s_add_i32 s38, s38, 2
	s_cmp_ge_i32 s38, s3
	s_cbranch_scc1 .Lg4_warm
	v_add_u32_e32 v246, v227, v228
	v_add_u32_e32 v247, v227, v231
	v_lshlrev_b32_e32 v246, 1, v246
	v_lshlrev_b32_e32 v247, 1, v247
	v_add_u32_e32 v248, 0x20000, v246
	v_add_u32_e32 v249, 0x40000, v246
	v_add_u32_e32 v250, 0x60000, v246
	v_add_u32_e32 v251, 0x20000, v247
	v_add_u32_e32 v252, 0x40000, v247
	v_add_u32_e32 v253, 0x60000, v247
	s_setprio 1
	s_waitcnt vmcnt(7)
	ds_write_b128 v254, v[100:103]
	global_load_dwordx4 v[100:103], v246, s[28:29] offset:256
	s_waitcnt lgkmcnt(8)
	v_mfma_f32_16x16x32_f16 v[156:159], v[176:179], v[192:195], v[156:159]
	s_waitcnt lgkmcnt(7)
	v_mfma_f32_16x16x32_f16 v[152:155], v[180:183], v[192:195], v[152:155]
	s_waitcnt lgkmcnt(6)
	v_mfma_f32_16x16x32_f16 v[140:143], v[184:187], v[192:195], v[140:143]
	s_waitcnt lgkmcnt(5)
	v_mfma_f32_16x16x32_f16 v[136:139], v[188:191], v[192:195], v[136:139]
	s_waitcnt vmcnt(7)
	ds_write_b128 v254, v[108:111] offset:1024
	global_load_dwordx4 v[108:111], v248, s[28:29] offset:256
	v_mfma_f32_16x16x32_f16 v[128:131], v[176:179], v[172:175], v[128:131]
	v_mfma_f32_16x16x32_f16 v[120:123], v[180:183], v[172:175], v[120:123]
	v_mfma_f32_16x16x32_f16 v[112:115], v[184:187], v[172:175], v[112:115]
	v_mfma_f32_16x16x32_f16 v[104:107], v[188:191], v[172:175], v[104:107]
	s_waitcnt vmcnt(7)
	ds_write_b128 v254, v[116:119] offset:2048
	global_load_dwordx4 v[116:119], v249, s[28:29] offset:256
	v_mfma_f32_16x16x32_f16 v[96:99], v[176:179], v[168:171], v[96:99]
	v_mfma_f32_16x16x32_f16 v[92:95], v[180:183], v[168:171], v[92:95]
	v_mfma_f32_16x16x32_f16 v[88:91], v[184:187], v[168:171], v[88:91]
	v_mfma_f32_16x16x32_f16 v[84:87], v[188:191], v[168:171], v[84:87]
	s_waitcnt vmcnt(7)
	ds_write_b128 v254, v[124:127] offset:3072
	global_load_dwordx4 v[124:127], v250, s[28:29] offset:256
	v_mfma_f32_16x16x32_f16 v[80:83], v[176:179], v[164:167], v[80:83]
	v_mfma_f32_16x16x32_f16 v[76:79], v[180:183], v[164:167], v[76:79]
	v_mfma_f32_16x16x32_f16 v[72:75], v[184:187], v[164:167], v[72:75]
	v_mfma_f32_16x16x32_f16 v[68:71], v[188:191], v[164:167], v[68:71]
	s_waitcnt vmcnt(7)
	ds_write_b128 v255, v[132:135]
	global_load_dwordx4 v[132:135], v247, s[30:31] offset:256
	s_waitcnt lgkmcnt(5)
	v_mfma_f32_16x16x32_f16 v[64:67], v[176:179], v[208:211], v[64:67]
	v_mfma_f32_16x16x32_f16 v[60:63], v[180:183], v[208:211], v[60:63]
	v_mfma_f32_16x16x32_f16 v[56:59], v[184:187], v[208:211], v[56:59]
	v_mfma_f32_16x16x32_f16 v[52:55], v[188:191], v[208:211], v[52:55]
	s_waitcnt vmcnt(7)
	ds_write_b128 v255, v[144:147] offset:1024
	global_load_dwordx4 v[144:147], v251, s[30:31] offset:256
	v_mfma_f32_16x16x32_f16 v[48:51], v[176:179], v[204:207], v[48:51]
	v_mfma_f32_16x16x32_f16 v[44:47], v[180:183], v[204:207], v[44:47]
	v_mfma_f32_16x16x32_f16 v[40:43], v[184:187], v[204:207], v[40:43]
	v_mfma_f32_16x16x32_f16 v[36:39], v[188:191], v[204:207], v[36:39]
	s_waitcnt vmcnt(7)
	ds_write_b128 v255, v[148:151] offset:2048
	global_load_dwordx4 v[148:151], v252, s[30:31] offset:256
	v_mfma_f32_16x16x32_f16 v[30:33], v[176:179], v[200:203], v[30:33]
	v_mfma_f32_16x16x32_f16 v[26:29], v[180:183], v[200:203], v[26:29]
	v_mfma_f32_16x16x32_f16 v[22:25], v[184:187], v[200:203], v[22:25]
	v_mfma_f32_16x16x32_f16 v[18:21], v[188:191], v[200:203], v[18:21]
	s_waitcnt vmcnt(7)
	ds_write_b128 v255, v[160:163] offset:3072
	global_load_dwordx4 v[160:163], v253, s[30:31] offset:256
	v_mfma_f32_16x16x32_f16 v[14:17], v[176:179], v[196:199], v[14:17]
	v_mfma_f32_16x16x32_f16 v[10:13], v[180:183], v[196:199], v[10:13]
	v_mfma_f32_16x16x32_f16 v[6:9], v[184:187], v[196:199], v[6:9]
	v_mfma_f32_16x16x32_f16 v[2:5], v[188:191], v[196:199], v[2:5]
	s_setprio 0
.Lg4_tail:
	s_addk_i32 s23, 0x800
	v_add_u32_e32 v231, 64, v231
	s_cmp_lg_u32 s3, s39
	v_add_u32_e32 v228, 64, v228
	s_waitcnt lgkmcnt(0)
	s_barrier
	s_cbranch_scc0 .LBB0_812
	s_mov_b32 s38, s39
	s_branch .LBB0_806
.Lg4_cold:
	s_setprio 1
	s_waitcnt lgkmcnt(7)
	v_mfma_f32_16x16x32_f16 v[156:159], v[176:179], v[192:195], v[156:159]
	s_waitcnt lgkmcnt(6)
	v_mfma_f32_16x16x32_f16 v[152:155], v[180:183], v[192:195], v[152:155]
	s_waitcnt lgkmcnt(5)
	v_mfma_f32_16x16x32_f16 v[140:143], v[184:187], v[192:195], v[140:143]
	s_waitcnt lgkmcnt(4)
	v_mfma_f32_16x16x32_f16 v[136:139], v[188:191], v[192:195], v[136:139]
	v_mfma_f32_16x16x32_f16 v[128:131], v[176:179], v[172:175], v[128:131]
	v_mfma_f32_16x16x32_f16 v[120:123], v[180:183], v[172:175], v[120:123]
	v_mfma_f32_16x16x32_f16 v[112:115], v[184:187], v[172:175], v[112:115]
	v_mfma_f32_16x16x32_f16 v[104:107], v[188:191], v[172:175], v[104:107]
	v_mfma_f32_16x16x32_f16 v[96:99], v[176:179], v[168:171], v[96:99]
	v_mfma_f32_16x16x32_f16 v[92:95], v[180:183], v[168:171], v[92:95]
	v_mfma_f32_16x16x32_f16 v[88:91], v[184:187], v[168:171], v[88:91]
	v_mfma_f32_16x16x32_f16 v[84:87], v[188:191], v[168:171], v[84:87]
	v_mfma_f32_16x16x32_f16 v[80:83], v[176:179], v[164:167], v[80:83]
	v_mfma_f32_16x16x32_f16 v[76:79], v[180:183], v[164:167], v[76:79]
	v_mfma_f32_16x16x32_f16 v[72:75], v[184:187], v[164:167], v[72:75]
	v_mfma_f32_16x16x32_f16 v[68:71], v[188:191], v[164:167], v[68:71]
	s_setprio 0
	s_setprio 1
	s_waitcnt lgkmcnt(3)
	v_mfma_f32_16x16x32_f16 v[64:67], v[176:179], v[208:211], v[64:67]
	v_mfma_f32_16x16x32_f16 v[60:63], v[180:183], v[208:211], v[60:63]
	v_mfma_f32_16x16x32_f16 v[56:59], v[184:187], v[208:211], v[56:59]
	v_mfma_f32_16x16x32_f16 v[52:55], v[188:191], v[208:211], v[52:55]
	s_waitcnt lgkmcnt(2)
	v_mfma_f32_16x16x32_f16 v[48:51], v[176:179], v[204:207], v[48:51]
	v_mfma_f32_16x16x32_f16 v[44:47], v[180:183], v[204:207], v[44:47]
	v_mfma_f32_16x16x32_f16 v[40:43], v[184:187], v[204:207], v[40:43]
	v_mfma_f32_16x16x32_f16 v[36:39], v[188:191], v[204:207], v[36:39]
	s_waitcnt lgkmcnt(1)
	v_mfma_f32_16x16x32_f16 v[30:33], v[176:179], v[200:203], v[30:33]
	v_mfma_f32_16x16x32_f16 v[26:29], v[180:183], v[200:203], v[26:29]
	v_mfma_f32_16x16x32_f16 v[22:25], v[184:187], v[200:203], v[22:25]
	v_mfma_f32_16x16x32_f16 v[18:21], v[188:191], v[200:203], v[18:21]
	s_waitcnt lgkmcnt(0)
	v_mfma_f32_16x16x32_f16 v[14:17], v[176:179], v[196:199], v[14:17]
	v_mfma_f32_16x16x32_f16 v[10:13], v[180:183], v[196:199], v[10:13]
	v_mfma_f32_16x16x32_f16 v[6:9], v[184:187], v[196:199], v[6:9]
	v_mfma_f32_16x16x32_f16 v[2:5], v[188:191], v[196:199], v[2:5]
	s_setprio 0
	s_branch .Lg4_tail
.Lg4_warm:
	s_waitcnt vmcnt(7)
	ds_write_b128 v254, v[100:103]
	s_waitcnt vmcnt(6)
	ds_write_b128 v254, v[108:111] offset:1024
	s_waitcnt vmcnt(5)
	ds_write_b128 v254, v[116:119] offset:2048
	s_waitcnt vmcnt(4)
	ds_write_b128 v254, v[124:127] offset:3072
	s_waitcnt vmcnt(3)
	ds_write_b128 v255, v[132:135]
	s_waitcnt vmcnt(2)
	ds_write_b128 v255, v[144:147] offset:1024
	s_waitcnt vmcnt(1)
	ds_write_b128 v255, v[148:151] offset:2048
	s_waitcnt vmcnt(0)
	ds_write_b128 v255, v[160:163] offset:3072
	s_setprio 1
	s_waitcnt lgkmcnt(15)
	v_mfma_f32_16x16x32_f16 v[156:159], v[176:179], v[192:195], v[156:159]
	s_waitcnt lgkmcnt(14)
	v_mfma_f32_16x16x32_f16 v[152:155], v[180:183], v[192:195], v[152:155]
	s_waitcnt lgkmcnt(13)
	v_mfma_f32_16x16x32_f16 v[140:143], v[184:187], v[192:195], v[140:143]
	s_waitcnt lgkmcnt(12)
	v_mfma_f32_16x16x32_f16 v[136:139], v[188:191], v[192:195], v[136:139]
	v_mfma_f32_16x16x32_f16 v[128:131], v[176:179], v[172:175], v[128:131]
	v_mfma_f32_16x16x32_f16 v[120:123], v[180:183], v[172:175], v[120:123]
	v_mfma_f32_16x16x32_f16 v[112:115], v[184:187], v[172:175], v[112:115]
	v_mfma_f32_16x16x32_f16 v[104:107], v[188:191], v[172:175], v[104:107]
	v_mfma_f32_16x16x32_f16 v[96:99], v[176:179], v[168:171], v[96:99]
	v_mfma_f32_16x16x32_f16 v[92:95], v[180:183], v[168:171], v[92:95]
	v_mfma_f32_16x16x32_f16 v[88:91], v[184:187], v[168:171], v[88:91]
	v_mfma_f32_16x16x32_f16 v[84:87], v[188:191], v[168:171], v[84:87]
	v_mfma_f32_16x16x32_f16 v[80:83], v[176:179], v[164:167], v[80:83]
	v_mfma_f32_16x16x32_f16 v[76:79], v[180:183], v[164:167], v[76:79]
	v_mfma_f32_16x16x32_f16 v[72:75], v[184:187], v[164:167], v[72:75]
	v_mfma_f32_16x16x32_f16 v[68:71], v[188:191], v[164:167], v[68:71]
	s_setprio 0
	s_setprio 1
	s_waitcnt lgkmcnt(11)
	v_mfma_f32_16x16x32_f16 v[64:67], v[176:179], v[208:211], v[64:67]
	v_mfma_f32_16x16x32_f16 v[60:63], v[180:183], v[208:211], v[60:63]
	v_mfma_f32_16x16x32_f16 v[56:59], v[184:187], v[208:211], v[56:59]
	v_mfma_f32_16x16x32_f16 v[52:55], v[188:191], v[208:211], v[52:55]
	s_waitcnt lgkmcnt(10)
	v_mfma_f32_16x16x32_f16 v[48:51], v[176:179], v[204:207], v[48:51]
	v_mfma_f32_16x16x32_f16 v[44:47], v[180:183], v[204:207], v[44:47]
	v_mfma_f32_16x16x32_f16 v[40:43], v[184:187], v[204:207], v[40:43]
	v_mfma_f32_16x16x32_f16 v[36:39], v[188:191], v[204:207], v[36:39]
	s_waitcnt lgkmcnt(9)
	v_mfma_f32_16x16x32_f16 v[30:33], v[176:179], v[200:203], v[30:33]
	v_mfma_f32_16x16x32_f16 v[26:29], v[180:183], v[200:203], v[26:29]
	v_mfma_f32_16x16x32_f16 v[22:25], v[184:187], v[200:203], v[22:25]
	v_mfma_f32_16x16x32_f16 v[18:21], v[188:191], v[200:203], v[18:21]
	s_waitcnt lgkmcnt(8)
	v_mfma_f32_16x16x32_f16 v[14:17], v[176:179], v[196:199], v[14:17]
	v_mfma_f32_16x16x32_f16 v[10:13], v[180:183], v[196:199], v[10:13]
	v_mfma_f32_16x16x32_f16 v[6:9], v[184:187], v[196:199], v[6:9]
	v_mfma_f32_16x16x32_f16 v[2:5], v[188:191], v[196:199], v[2:5]
	s_setprio 0
	s_branch .Lg4_tail

	.amdhsa_kernel _Z4mega6Params
		.amdhsa_group_segment_fixed_size 0
		.amdhsa_private_segment_fixed_size 0
		.amdhsa_kernarg_size 520
		.amdhsa_user_sgpr_count 2
		.amdhsa_user_sgpr_dispatch_ptr 0
		.amdhsa_user_sgpr_queue_ptr 0
		.amdhsa_user_sgpr_kernarg_segment_ptr 1
		.amdhsa_user_sgpr_dispatch_id 0
		.amdhsa_user_sgpr_kernarg_preload_length 0
		.amdhsa_user_sgpr_kernarg_preload_offset 0
		.amdhsa_user_sgpr_private_segment_size 0
		.amdhsa_uses_dynamic_stack 0
		.amdhsa_enable_private_segment 0
		.amdhsa_system_sgpr_workgroup_id_x 1
		.amdhsa_system_sgpr_workgroup_id_y 0
		.amdhsa_system_sgpr_workgroup_id_z 0
		.amdhsa_system_sgpr_workgroup_info 0
		.amdhsa_system_vgpr_workitem_id 2
		.amdhsa_next_free_vgpr 256
		.amdhsa_next_free_sgpr 98
		.amdhsa_accum_offset 256
		.amdhsa_reserve_vcc 1
		.amdhsa_float_round_mode_32 0
		.amdhsa_float_round_mode_16_64 0
		.amdhsa_float_denorm_mode_32 3
		.amdhsa_float_denorm_mode_16_64 3
		.amdhsa_dx10_clamp 1
		.amdhsa_ieee_mode 1
		.amdhsa_fp16_overflow 0
		.amdhsa_tg_split 0
		.amdhsa_exception_fp_ieee_invalid_op 0
		.amdhsa_exception_fp_denorm_src 0
		.amdhsa_exception_fp_ieee_div_zero 0
		.amdhsa_exception_fp_ieee_overflow 0
		.amdhsa_exception_fp_ieee_underflow 0
		.amdhsa_exception_fp_ieee_inexact 0
		.amdhsa_exception_int_div_zero 0
	.end_amdhsa_kernel

amdhsa.kernels:
  - .agpr_count:     0
    .args:
      - .offset:         0
        .size:           264
        .value_kind:     by_value
      - .offset:         264
        .size:           4
        .value_kind:     hidden_block_count_x
      - .offset:         268
        .size:           4
        .value_kind:     hidden_block_count_y
      - .offset:         272
        .size:           4
        .value_kind:     hidden_block_count_z
      - .offset:         276
        .size:           2
        .value_kind:     hidden_group_size_x
      - .offset:         278
        .size:           2
        .value_kind:     hidden_group_size_y
      - .offset:         280
        .size:           2
        .value_kind:     hidden_group_size_z
      - .offset:         282
        .size:           2
        .value_kind:     hidden_remainder_x
      - .offset:         284
        .size:           2
        .value_kind:     hidden_remainder_y
      - .offset:         286
        .size:           2
        .value_kind:     hidden_remainder_z
      - .offset:         304
        .size:           8
        .value_kind:     hidden_global_offset_x
      - .offset:         312
        .size:           8
        .value_kind:     hidden_global_offset_y
      - .offset:         320
        .size:           8
        .value_kind:     hidden_global_offset_z
      - .offset:         328
        .size:           2
        .value_kind:     hidden_grid_dims
      - .offset:         352
        .size:           8
        .value_kind:     hidden_multigrid_sync_arg
      - .offset:         384
        .size:           4
        .value_kind:     hidden_dynamic_lds_size
    .group_segment_fixed_size: 0
    .kernarg_segment_align: 8
    .kernarg_segment_size: 520
    .language:       OpenCL C
    .language_version:
      - 2
      - 0
    .max_flat_workgroup_size: 512
    .name:           _Z4mega6Params
    .private_segment_fixed_size: 0
    .sgpr_count:     104
    .sgpr_spill_count: 83
    .symbol:         _Z4mega6Params.kd
    .uniform_work_group_size: 1
    .uses_dynamic_stack: false
    .vgpr_count:     256
    .vgpr_spill_count: 0
    .wavefront_size: 64
